# EpiFinal tail: the four gain loads issued before the rstd slot exchange (were after the second barrier); slot partials via one dwordx4
# baseline (speedup 1.0000x reference)
.LBB0_708:
	s_waitcnt vmcnt(0) lgkmcnt(0)
	s_barrier
	s_lshl_b32 s33, s40, 8
	s_lshl_b32 s12, s34, 8
	s_or_b32 s12, s12, s43
	v_readlane_b32 s10, v252, 11
	v_readlane_b32 s11, v252, 12
	v_lshl_add_u32 v140, v165, 3, s12
	v_ashrrev_i32_e32 v141, 31, v140
	v_lshlrev_b64 v[140:141], 2, v[140:141]
	v_lshl_add_u64 v[140:141], s[10:11], 0, v[140:141]
	global_load_dwordx4 v[136:139], v[140:141], off offset:16
	global_load_dwordx4 v[144:147], v[140:141], off
	global_load_dwordx4 v[132:135], v[140:141], off offset:528
	global_load_dwordx4 v[140:143], v[140:141], off offset:512
	s_and_saveexec_b64 s[2:3], s[0:1]
	s_cbranch_execz .LBB0_710
	s_waitcnt lgkmcnt(0)
	v_add_u32_e32 v148, s33, v18
	v_readlane_b32 s0, v248, 59
	v_ashrrev_i32_e32 v149, 31, v148
	v_readlane_b32 s1, v248, 60
	v_lshl_add_u32 v18, v18, 2, 0
	v_add_u32_e32 v18, 0x21200, v18
	v_lshl_add_u64 v[148:149], v[148:149], 4, s[0:1]
	global_load_dwordx4 v[148:151], v[148:149], off sc1
	s_waitcnt vmcnt(0)
	v_add_f32_e32 v19, 0, v148
	v_add_f32_e32 v19, v19, v149
	v_add_f32_e32 v19, v19, v150
	v_add_f32_e32 v19, v19, v151
	v_fmamk_f32 v19, v19, 0x3a800000, v218
	v_rsq_f32_e32 v19, v19
	ds_write_b32 v18, v19
.LBB0_710:
	s_or_b64 exec, exec, s[2:3]
	s_lshl_b32 s0, s34, 8
	s_or_b32 s0, s0, s43
	v_lshl_add_u32 v18, v165, 3, s0
	v_ashrrev_i32_e32 v19, 31, v18
	v_readlane_b32 s0, v252, 1
	v_lshlrev_b64 v[18:19], 2, v[18:19]
	v_readlane_b32 s10, v252, 11
	v_readlane_b32 s11, v252, 12
	s_waitcnt lgkmcnt(0)
	s_barrier
	s_add_i32 s0, 0, 0x21200
	s_waitcnt lgkmcnt(0)
	v_lshl_add_u32 v156, v155, 2, s0
	ds_read2st64_b32 v[150:151], v156 offset1:2
	ds_read2_b32 v[152:153], v17 offset1:16
	v_readlane_b32 s12, v252, 13
	v_readlane_b32 s13, v252, 14
	v_readlane_b32 s1, v252, 2
	v_readlane_b32 s2, v252, 3
	s_waitcnt lgkmcnt(0)
	v_rcp_f32_e32 v148, v152
	v_rcp_f32_e32 v152, v153
	v_readlane_b32 s3, v252, 4
	v_readlane_b32 s4, v252, 5
	v_mul_f32_e32 v150, v150, v148
	v_add_u32_e32 v148, s33, v155
	v_ashrrev_i32_e32 v149, 31, v148
	v_lshlrev_b64 v[158:159], 12, v[148:149]
	v_lshl_add_u64 v[158:159], s[12:13], 0, v[158:159]
	v_lshl_add_u64 v[162:163], v[158:159], 0, v[18:19]
	v_pk_mul_f32 v[158:159], v[10:11], v[150:151] op_sel_hi:[1,0]
	v_pk_mul_f32 v[166:167], v[8:9], v[150:151] op_sel_hi:[1,0]
	v_or_b32_e32 v149, 16, v155
	v_readlane_b32 s5, v252, 6
	v_readlane_b32 s6, v252, 7
	v_readlane_b32 s7, v252, 8
	v_readlane_b32 s8, v252, 9
	v_readlane_b32 s9, v252, 10
	v_readlane_b32 s14, v252, 15
	v_readlane_b32 s15, v252, 16
	s_waitcnt vmcnt(0)
	v_pk_mul_f32 v[160:161], v[146:147], v[158:159]
	v_pk_mul_f32 v[158:159], v[144:145], v[166:167]
	global_store_dwordx4 v[162:163], v[158:161], off
	v_pk_mul_f32 v[166:167], v[12:13], v[150:151] op_sel_hi:[1,0]
	s_nop 0
	v_pk_mul_f32 v[158:159], v[14:15], v[150:151] op_sel_hi:[1,0]
	s_nop 0
	v_pk_mul_f32 v[160:161], v[138:139], v[158:159]
	v_pk_mul_f32 v[158:159], v[136:137], v[166:167]
	global_store_dwordx4 v[162:163], v[158:161], off offset:16
	v_pk_mul_f32 v[166:167], v[0:1], v[150:151] op_sel_hi:[1,0]
	s_nop 0
	v_pk_mul_f32 v[158:159], v[2:3], v[150:151] op_sel_hi:[1,0]
	s_nop 0
	v_pk_mul_f32 v[160:161], v[142:143], v[158:159]
	v_pk_mul_f32 v[158:159], v[140:141], v[166:167]
	global_store_dwordx4 v[162:163], v[158:161], off offset:512
	v_pk_mul_f32 v[166:167], v[4:5], v[150:151] op_sel_hi:[1,0]
	s_nop 0
	v_pk_mul_f32 v[158:159], v[6:7], v[150:151] op_sel_hi:[1,0]
	v_lshl_add_u32 v150, v149, 2, s0
	ds_read_b32 v150, v150
	v_pk_mul_f32 v[160:161], v[134:135], v[158:159]
	v_pk_mul_f32 v[158:159], v[132:133], v[166:167]
	global_store_dwordx4 v[162:163], v[158:161], off offset:528
	s_waitcnt lgkmcnt(0)
	v_mul_f32_e32 v150, v150, v152
	v_add_u32_e32 v152, s33, v149
	v_ashrrev_i32_e32 v153, 31, v152
	v_lshlrev_b64 v[152:153], 12, v[152:153]
	v_lshl_add_u64 v[152:153], s[12:13], 0, v[152:153]
	v_pk_mul_f32 v[160:161], v[30:31], v[150:151] op_sel_hi:[1,0]
	v_pk_mul_f32 v[158:159], v[28:29], v[150:151] op_sel_hi:[1,0]
	v_lshl_add_u64 v[152:153], v[152:153], 0, v[18:19]
	v_pk_mul_f32 v[158:159], v[144:145], v[158:159]
	v_pk_mul_f32 v[160:161], v[146:147], v[160:161]
	global_store_dwordx4 v[152:153], v[158:161], off
	v_or_b32_e32 v149, 32, v155
	s_nop 0
	v_pk_mul_f32 v[160:161], v[34:35], v[150:151] op_sel_hi:[1,0]
	v_pk_mul_f32 v[158:159], v[32:33], v[150:151] op_sel_hi:[1,0]
	v_pk_mul_f32 v[160:161], v[138:139], v[160:161]
	v_pk_mul_f32 v[158:159], v[136:137], v[158:159]
	global_store_dwordx4 v[152:153], v[158:161], off offset:16
	s_nop 1
	v_pk_mul_f32 v[160:161], v[22:23], v[150:151] op_sel_hi:[1,0]
	v_pk_mul_f32 v[158:159], v[20:21], v[150:151] op_sel_hi:[1,0]
	v_pk_mul_f32 v[160:161], v[142:143], v[160:161]
	v_pk_mul_f32 v[158:159], v[140:141], v[158:159]
	global_store_dwordx4 v[152:153], v[158:161], off offset:512
	s_nop 1
	v_pk_mul_f32 v[160:161], v[26:27], v[150:151] op_sel_hi:[1,0]
	v_pk_mul_f32 v[158:159], v[24:25], v[150:151] op_sel_hi:[1,0]
	v_pk_mul_f32 v[160:161], v[134:135], v[160:161]
	v_pk_mul_f32 v[158:159], v[132:133], v[158:159]
	global_store_dwordx4 v[152:153], v[158:161], off offset:528
	v_lshl_add_u32 v150, v149, 2, s0
	ds_read_b32 v150, v150
	ds_read2_b32 v[152:153], v17 offset0:32 offset1:48
	v_add_u32_e32 v158, s33, v149
	v_ashrrev_i32_e32 v159, 31, v158
	v_lshlrev_b64 v[158:159], 12, v[158:159]
	v_lshl_add_u64 v[158:159], s[12:13], 0, v[158:159]
	s_waitcnt lgkmcnt(0)
	v_rcp_f32_e32 v152, v152
	v_lshl_add_u64 v[162:163], v[158:159], 0, v[18:19]
	v_or_b32_e32 v149, 48, v155
	v_mul_f32_e32 v150, v150, v152
	v_pk_mul_f32 v[160:161], v[38:39], v[150:151] op_sel_hi:[1,0]
	v_pk_mul_f32 v[158:159], v[36:37], v[150:151] op_sel_hi:[1,0]
	v_pk_mul_f32 v[160:161], v[146:147], v[160:161]
	v_pk_mul_f32 v[158:159], v[144:145], v[158:159]
	global_store_dwordx4 v[162:163], v[158:161], off
	v_rcp_f32_e32 v152, v153
	s_nop 0
	v_pk_mul_f32 v[160:161], v[46:47], v[150:151] op_sel_hi:[1,0]
	v_pk_mul_f32 v[158:159], v[44:45], v[150:151] op_sel_hi:[1,0]
	v_pk_mul_f32 v[160:161], v[138:139], v[160:161]
	v_pk_mul_f32 v[158:159], v[136:137], v[158:159]
	global_store_dwordx4 v[162:163], v[158:161], off offset:16
	s_nop 1
	v_pk_mul_f32 v[160:161], v[42:43], v[150:151] op_sel_hi:[1,0]
	v_pk_mul_f32 v[158:159], v[40:41], v[150:151] op_sel_hi:[1,0]
	v_pk_mul_f32 v[160:161], v[142:143], v[160:161]
	v_pk_mul_f32 v[158:159], v[140:141], v[158:159]
	global_store_dwordx4 v[162:163], v[158:161], off offset:512
	s_nop 1
	v_pk_mul_f32 v[160:161], v[50:51], v[150:151] op_sel_hi:[1,0]
	v_pk_mul_f32 v[158:159], v[48:49], v[150:151] op_sel_hi:[1,0]
	v_lshl_add_u32 v150, v149, 2, s0
	ds_read_b32 v150, v150
	v_pk_mul_f32 v[158:159], v[132:133], v[158:159]
	v_pk_mul_f32 v[160:161], v[134:135], v[160:161]
	global_store_dwordx4 v[162:163], v[158:161], off offset:528
	s_mov_b64 s[0:1], 0
	s_waitcnt lgkmcnt(0)
	v_mul_f32_e32 v150, v150, v152
	v_add_u32_e32 v152, s33, v149
	v_ashrrev_i32_e32 v153, 31, v152
	v_lshlrev_b64 v[152:153], 12, v[152:153]
	v_lshl_add_u64 v[152:153], s[12:13], 0, v[152:153]
	v_pk_mul_f32 v[158:159], v[80:81], v[150:151] op_sel_hi:[1,0]
	v_pk_mul_f32 v[160:161], v[82:83], v[150:151] op_sel_hi:[1,0]
	v_lshl_add_u64 v[152:153], v[152:153], 0, v[18:19]
	v_pk_mul_f32 v[160:161], v[146:147], v[160:161]
	v_pk_mul_f32 v[158:159], v[144:145], v[158:159]
	global_store_dwordx4 v[152:153], v[158:161], off
	s_nop 1
	v_pk_mul_f32 v[158:159], v[88:89], v[150:151] op_sel_hi:[1,0]
	v_pk_mul_f32 v[160:161], v[90:91], v[150:151] op_sel_hi:[1,0]
	v_pk_mul_f32 v[158:159], v[136:137], v[158:159]
	v_pk_mul_f32 v[160:161], v[138:139], v[160:161]
	global_store_dwordx4 v[152:153], v[158:161], off offset:16
	s_nop 1
	v_pk_mul_f32 v[158:159], v[60:61], v[150:151] op_sel_hi:[1,0]
	v_pk_mul_f32 v[160:161], v[62:63], v[150:151] op_sel_hi:[1,0]
	v_pk_mul_f32 v[158:159], v[140:141], v[158:159]
	v_pk_mul_f32 v[160:161], v[142:143], v[160:161]
	global_store_dwordx4 v[152:153], v[158:161], off offset:512
	s_nop 1
	v_pk_mul_f32 v[158:159], v[64:65], v[150:151] op_sel_hi:[1,0]
	v_pk_mul_f32 v[160:161], v[66:67], v[150:151] op_sel_hi:[1,0]
	v_pk_mul_f32 v[158:159], v[132:133], v[158:159]
	v_pk_mul_f32 v[160:161], v[134:135], v[160:161]
	global_store_dwordx4 v[152:153], v[158:161], off offset:528
	ds_read2_b32 v[158:159], v17 offset0:64 offset1:80
	v_add_u32_e32 v150, s33, v157
	s_waitcnt lgkmcnt(0)
	v_rcp_f32_e32 v149, v158
	s_nop 0
	v_mul_f32_e32 v158, v151, v149
	v_ashrrev_i32_e32 v151, 31, v150
	v_lshlrev_b64 v[150:151], 12, v[150:151]
	v_lshl_add_u64 v[150:151], s[12:13], 0, v[150:151]
	v_lshl_add_u64 v[160:161], v[150:151], 0, v[18:19]
	v_pk_mul_f32 v[150:151], v[70:71], v[158:159] op_sel_hi:[1,0]
	v_pk_mul_f32 v[162:163], v[68:69], v[158:159] op_sel_hi:[1,0]
	v_pk_mul_f32 v[152:153], v[146:147], v[150:151]
	v_pk_mul_f32 v[150:151], v[144:145], v[162:163]
	global_store_dwordx4 v[160:161], v[150:153], off
	v_pk_mul_f32 v[162:163], v[72:73], v[158:159] op_sel_hi:[1,0]
	v_rcp_f32_e32 v149, v159
	v_pk_mul_f32 v[150:151], v[74:75], v[158:159] op_sel_hi:[1,0]
	s_nop 0
	v_pk_mul_f32 v[152:153], v[138:139], v[150:151]
	v_pk_mul_f32 v[150:151], v[136:137], v[162:163]
	global_store_dwordx4 v[160:161], v[150:153], off offset:16
	v_pk_mul_f32 v[162:163], v[52:53], v[158:159] op_sel_hi:[1,0]
	s_nop 0
	v_pk_mul_f32 v[150:151], v[54:55], v[158:159] op_sel_hi:[1,0]
	s_nop 0
	v_pk_mul_f32 v[152:153], v[142:143], v[150:151]
	v_pk_mul_f32 v[150:151], v[140:141], v[162:163]
	global_store_dwordx4 v[160:161], v[150:153], off offset:512
	v_pk_mul_f32 v[162:163], v[56:57], v[158:159] op_sel_hi:[1,0]
	s_nop 0
	v_pk_mul_f32 v[150:151], v[58:59], v[158:159] op_sel_hi:[1,0]
	s_nop 0
	v_pk_mul_f32 v[152:153], v[134:135], v[150:151]
	v_pk_mul_f32 v[150:151], v[132:133], v[162:163]
	global_store_dwordx4 v[160:161], v[150:153], off offset:528
	ds_read2_b32 v[160:161], v156 offset0:144 offset1:160
	s_waitcnt lgkmcnt(0)
	v_mul_f32_e32 v158, v160, v149
	v_add_u32_e32 v150, 0x90, v148
	v_ashrrev_i32_e32 v151, 31, v150
	v_lshlrev_b64 v[150:151], 12, v[150:151]
	v_lshl_add_u64 v[150:151], s[12:13], 0, v[150:151]
	v_lshl_add_u64 v[162:163], v[150:151], 0, v[18:19]
	v_pk_mul_f32 v[150:151], v[94:95], v[158:159] op_sel_hi:[1,0]
	v_pk_mul_f32 v[166:167], v[92:93], v[158:159] op_sel_hi:[1,0]
	v_pk_mul_f32 v[152:153], v[146:147], v[150:151]
	v_pk_mul_f32 v[150:151], v[144:145], v[166:167]
	global_store_dwordx4 v[162:163], v[150:153], off
	v_pk_mul_f32 v[166:167], v[96:97], v[158:159] op_sel_hi:[1,0]
	s_nop 0
	v_pk_mul_f32 v[150:151], v[98:99], v[158:159] op_sel_hi:[1,0]
	s_nop 0
	v_pk_mul_f32 v[152:153], v[138:139], v[150:151]
	v_pk_mul_f32 v[150:151], v[136:137], v[166:167]
	global_store_dwordx4 v[162:163], v[150:153], off offset:16
	v_pk_mul_f32 v[166:167], v[76:77], v[158:159] op_sel_hi:[1,0]
	s_nop 0
	v_pk_mul_f32 v[150:151], v[78:79], v[158:159] op_sel_hi:[1,0]
	s_nop 0
	v_pk_mul_f32 v[152:153], v[142:143], v[150:151]
	v_pk_mul_f32 v[150:151], v[140:141], v[166:167]
	global_store_dwordx4 v[162:163], v[150:153], off offset:512
	s_nop 1
	v_pk_mul_f32 v[150:151], v[86:87], v[158:159] op_sel_hi:[1,0]
	v_pk_mul_f32 v[158:159], v[84:85], v[158:159] op_sel_hi:[1,0]
	v_pk_mul_f32 v[152:153], v[134:135], v[150:151]
	v_pk_mul_f32 v[150:151], v[132:133], v[158:159]
	global_store_dwordx4 v[162:163], v[150:153], off offset:528
	ds_read2_b32 v[150:151], v17 offset0:96 offset1:112
	s_waitcnt lgkmcnt(0)
	v_rcp_f32_e32 v17, v150
	v_add_u32_e32 v152, 0xa0, v148
	v_ashrrev_i32_e32 v153, 31, v152
	v_lshlrev_b64 v[152:153], 12, v[152:153]
	v_mul_f32_e32 v150, v161, v17
	v_lshl_add_u64 v[152:153], s[12:13], 0, v[152:153]
	v_pk_mul_f32 v[158:159], v[110:111], v[150:151] op_sel_hi:[1,0]
	v_pk_mul_f32 v[162:163], v[108:109], v[150:151] op_sel_hi:[1,0]
	v_lshl_add_u64 v[152:153], v[152:153], 0, v[18:19]
	v_pk_mul_f32 v[160:161], v[146:147], v[158:159]
	v_pk_mul_f32 v[158:159], v[144:145], v[162:163]
	ds_read_b32 v17, v156 offset:704
	global_store_dwordx4 v[152:153], v[158:161], off
	v_pk_mul_f32 v[162:163], v[112:113], v[150:151] op_sel_hi:[1,0]
	v_rcp_f32_e32 v149, v151
	v_pk_mul_f32 v[158:159], v[114:115], v[150:151] op_sel_hi:[1,0]
	v_add_u32_e32 v148, 0xb0, v148
	v_pk_mul_f32 v[160:161], v[138:139], v[158:159]
	v_pk_mul_f32 v[158:159], v[136:137], v[162:163]
	global_store_dwordx4 v[152:153], v[158:161], off offset:16
	v_pk_mul_f32 v[162:163], v[100:101], v[150:151] op_sel_hi:[1,0]
	s_nop 0
	v_pk_mul_f32 v[158:159], v[102:103], v[150:151] op_sel_hi:[1,0]
	s_nop 0
	v_pk_mul_f32 v[160:161], v[142:143], v[158:159]
	v_pk_mul_f32 v[158:159], v[140:141], v[162:163]
	global_store_dwordx4 v[152:153], v[158:161], off offset:512
	v_pk_mul_f32 v[162:163], v[104:105], v[150:151] op_sel_hi:[1,0]
	s_nop 0
	v_pk_mul_f32 v[158:159], v[106:107], v[150:151] op_sel_hi:[1,0]
	s_waitcnt lgkmcnt(0)
	v_mul_f32_e32 v150, v17, v149
	v_ashrrev_i32_e32 v149, 31, v148
	v_lshlrev_b64 v[148:149], 12, v[148:149]
	v_pk_mul_f32 v[160:161], v[134:135], v[158:159]
	v_pk_mul_f32 v[158:159], v[132:133], v[162:163]
	v_lshl_add_u64 v[148:149], s[12:13], 0, v[148:149]
	global_store_dwordx4 v[152:153], v[158:161], off offset:528
	v_lshl_add_u64 v[18:19], v[148:149], 0, v[18:19]
	v_pk_mul_f32 v[148:149], v[126:127], v[150:151] op_sel_hi:[1,0]
	v_pk_mul_f32 v[152:153], v[124:125], v[150:151] op_sel_hi:[1,0]
	v_pk_mul_f32 v[146:147], v[146:147], v[148:149]
	v_pk_mul_f32 v[144:145], v[144:145], v[152:153]
	global_store_dwordx4 v[18:19], v[144:147], off
	s_nop 1
	v_pk_mul_f32 v[144:145], v[130:131], v[150:151] op_sel_hi:[1,0]
	v_pk_mul_f32 v[146:147], v[128:129], v[150:151] op_sel_hi:[1,0]
	v_pk_mul_f32 v[138:139], v[138:139], v[144:145]
	v_pk_mul_f32 v[136:137], v[136:137], v[146:147]
	global_store_dwordx4 v[18:19], v[136:139], off offset:16
	v_pk_mul_f32 v[144:145], v[116:117], v[150:151] op_sel_hi:[1,0]
	s_nop 0
	v_pk_mul_f32 v[136:137], v[118:119], v[150:151] op_sel_hi:[1,0]
	s_nop 0
	v_pk_mul_f32 v[138:139], v[142:143], v[136:137]
	v_pk_mul_f32 v[136:137], v[140:141], v[144:145]
	global_store_dwordx4 v[18:19], v[136:139], off offset:512
	s_nop 1
	v_pk_mul_f32 v[136:137], v[122:123], v[150:151] op_sel_hi:[1,0]
	v_pk_mul_f32 v[138:139], v[120:121], v[150:151] op_sel_hi:[1,0]
	v_pk_mul_f32 v[134:135], v[134:135], v[136:137]
	v_pk_mul_f32 v[132:133], v[132:133], v[138:139]
	global_store_dwordx4 v[18:19], v[132:135], off offset:528
